# scan: coalesced x and B loads (row-major mapping, per-row w via ds_bpermute) and [chunk][head][row] DT layout
# speedup vs baseline: 1.0294x; 1.0294x over previous
; #define LAS __attribute__((address_space(3)))
; __device__ __forceinline__ unsigned pk2(float lo, float hi) { unsigned r; asm volatile("v_cvt_pk_bf16_f32 %0, %1, %2" : "=v"(r) : "v"(lo), "v"(hi)); return r; }
; template <bool DRY>
; __device__ __forceinline__ void ssd_chunk(SsdRegs& R, f32x4 (&st)[2], LAS unsigned char* L, bf16_t* BIG, const float* DT, float* SSQY, const SsdItem& I, int c, int tid, int lane, int wave, int li, int pi, int c16, int q4) {
;     ...
;         const int id = tid + 512 * i; *(LAS u32x4*)(L + CS + (id >> 4) * PC + (id & 15) * 16) = (u32x4){R.rc[i].x, R.rc[i].y, R.rc[i].z, R.rc[i].w};
;         const int n8 = wave + 8 * i; *(LAS u32x4*)(L + BS + lane * PC + n8 * 16) = (u32x4){R.rb[i].x, R.rb[i].y, R.rb[i].z, R.rb[i].w};
;         float f[8]; unpack8(R.rb[i], f);
;         u32x4 bwv; bwv.x = pk2(f[0] * wl, f[1] * wl); bwv.y = pk2(f[2] * wl, f[3] * wl); bwv.z = pk2(f[4] * wl, f[5] * wl); bwv.w = pk2(f[6] * wl, f[7] * wl);
;         *(LAS u32x4*)(L + BW + lane * PB + n8 * 16) = bwv;
;     }
;     if (wave < 4) *(LAS u32x4*)(L + XI + lane * PX + wave * 16) = (u32x4){R.rx.x, R.rx.y, R.rx.z, R.rx.w};
; template <bool DRY>
; __device__ __forceinline__ void phase_ssd_scan(const Args& a, int j, unsigned char* lds_raw) {
;     ...
;     const int tid = opaque_tid(), lane = tid & 63, wave = __builtin_amdgcn_readfirstlane(tid >> 6);
;     const int role = (wave == 1) ? 6 : ((wave == 6) ? 1 : wave);
;     const int c16 = lane & 15, q4 = lane >> 4, li = role >> 1, pi = role & 1;
;     for (int it = blockIdx.x; it < 256; it += gridDim.x) {
;         const int xc = it & 7, slot = it >> 3, pair = xc + 8 * (slot >> 3), sub = slot & 7;
;         SsdItem I; I.b = pair >> 3; I.g = pair & 7; I.h = I.g * 4 + (sub >> 1); I.ph = sub & 1;
;         I.Ah = -__expf(A_log[I.h]); I.Dh = Dp[I.h];
; #pragma unroll
;         for (int i = 0; i < 2; ++i) { I.offB[i] = (unsigned)(lane * BIGW + 4096 + I.g * 128 + (wave + 8 * i) * 8) * 2u; const int id = tid + 512 * i; I.offC[i] = (unsigned)((id >> 4) * BIGW + 5120 + I.g * 128 + (id & 15) * 8) * 2u; }
;         I.offX = (unsigned)(lane * BIGW + DI_ + I.h * 64 + I.ph * 32 + wave * 8) * 2u;
;         I.offZ = (unsigned)((16 * li + c16) * BIGW + I.h * 64 + I.ph * 32 + 16 * pi + 4 * q4) * 2u;
;         I.offDT = (unsigned)(lane * 32 + I.h) * 4u;
.LBB0_705:
	s_cmp_lt_i32 s74, 2
	s_mov_b64 s[0:1], -1
	s_cbranch_scc1 .LBB0_752
	s_cmp_eq_u32 s74, 2
	s_cbranch_scc0 .LBB0_751
	v_readlane_b32 s0, v253, 63
	s_waitcnt vmcnt(0) lgkmcnt(0)
	v_mov_b32_e32 v2, v0
	v_readlane_b32 s1, v254, 0
	s_andn2_b64 vcc, exec, s[0:1]
	v_readfirstlane_b32 s0, v2
	s_cbranch_vccnz .LBB0_751
	s_cmp_eq_u32 s27, 0x100
	s_cselect_b32 s100, 2, 7
	s_cselect_b32 s101, 8, 2
	v_writelane_b32 v255, s74, 31
	v_writelane_b32 v255, s69, 32
	s_mov_b32 s2, s22
	v_writelane_b32 v255, s2, 12
	v_and_b32_e32 v5, 63, v2
	v_mov_b32_e32 v1, 0x1000
	v_writelane_b32 v255, s3, 13
	s_lshl_b32 s2, s22, 5
	s_ashr_i32 s3, s2, 31
	s_lshl_b64 s[2:3], s[2:3], 2
	s_waitcnt lgkmcnt(0)
	s_add_u32 s4, s54, s2
	s_addc_u32 s5, s55, s3
	s_add_u32 s2, s56, s2
	s_addc_u32 s3, s57, s3
	s_ashr_i32 s0, s0, 6
	s_cmp_lg_u32 s0, 6
	v_writelane_b32 v255, s4, 10
	s_cselect_b32 s1, s0, 1
	s_cmp_lg_u32 s0, 1
	v_writelane_b32 v255, s5, 11
	s_cselect_b32 s1, s1, 6
	v_writelane_b32 v255, s2, 22
	s_and_b32 s19, s1, 1
	s_ashr_i32 s1, s1, 1
	v_writelane_b32 v255, s3, 23
	s_lshl_b32 s36, s0, 4
	s_lshl_b32 s2, s19, 5
	s_cmp_lt_i32 s0, 4
	s_cselect_b64 s[4:5], -1, 0
	s_movk_i32 s22, 0x1800
	v_writelane_b32 v255, s4, 20
	s_cmp_gt_i32 s0, 3
	v_mad_u32_u24 v4, v5, s22, v1
	v_writelane_b32 v255, s5, 21
	s_cselect_b64 s[4:5], -1, 0
	v_bfe_u32 v10, v2, 4, 2
	v_lshl_add_u32 v1, s0, 3, v4
	v_writelane_b32 v255, s4, 24
	s_lshl_b32 s3, s0, 9
	s_lshl_b32 s0, s0, 5
	v_readlane_b32 s18, v254, 51
	v_lshlrev_b32_e32 v15, 3, v10
	v_writelane_b32 v255, s5, 25
	s_add_i32 s3, s3, 0
	s_add_i32 s4, s18, s0
	s_add_i32 s3, s3, 0x16800
	v_add_u32_e32 v19, s4, v15
	s_add_i32 s20, s36, 0
	s_add_i32 s4, s2, 0
	s_lshl_b32 s14, s19, 1
	v_and_b32_e32 v11, 15, v2
	v_mul_u32_u24_e32 v12, 0x1800, v5
	s_cmp_le_i32 s14, s1
	v_add3_u32 v108, v4, v12, s36
	v_lshl_or_b32 v4, s1, 4, v11
	v_add_u32_e32 v20, s4, v15
	s_movk_i32 s4, 0x90
	s_cselect_b64 s[88:89], -1, 0
	s_cmp_eq_u32 s14, s1
	v_mul_lo_u32 v32, v4, s4
	s_cselect_b64 s[4:5], -1, 0
	s_lshl_b32 s68, s19, 6
	s_or_b32 s16, s14, 1
	s_cmp_ge_i32 s14, s1
	s_movk_i32 s24, 0x110
	s_cselect_b64 s[84:85], -1, 0
	s_cmp_eq_u32 s16, s1
	v_lshlrev_b32_e32 v13, 3, v2
	v_mad_u32_u24 v110, v5, s24, 0
	v_ashrrev_i32_e32 v24, 4, v2
	v_add_u32_e32 v26, 0x200, v2
	v_and_b32_e32 v111, 48, v2
	s_cselect_b64 s[14:15], -1, 0
	s_lshl_b32 s69, s16, 5
	v_mov_b32_e32 v36, s18
	s_movk_i32 s18, 0x60
	v_readlane_b32 s25, v254, 52
	v_and_b32_e32 v14, 0x78, v13
	v_lshlrev_b32_e32 v109, s100, v5
	v_lshlrev_b32_e32 v18, 2, v5
	v_lshl_add_u32 v23, v5, 4, v110
	v_ashrrev_i32_e32 v26, 4, v26
	v_mul_u32_u24_e32 v29, 0x60, v5
	v_lshl_or_b32 v33, s19, 7, v111
	s_cmp_eq_u32 s19, 0
	v_writelane_b32 v255, s19, 18
	v_lshl_or_b32 v35, s19, 4, v11
	v_mul_lo_u32 v37, v4, s18
	v_cmp_gt_u32_e64 s[18:19], 16, v5
	v_mov_b32_e32 v5, s25
	v_mul_lo_u32 v114, v24, s22
	v_lshlrev_b32_e32 v10, 2, v10
	v_mad_u32_u24 v36, v35, s24, v36
	v_mad_u32_u24 v35, v35, s24, v5
	v_mul_lo_u32 v115, v26, s22
	v_or_b32_e32 v5, v114, v14
	v_bfe_u32 v17, v2, 2, 2
	v_and_b32_e32 v13, 24, v13
	v_cmp_gt_u32_e64 s[6:7], v10, v11
	v_cmp_lt_u32_e64 s[8:9], v10, v11
	v_or_b32_e32 v34, 2, v10
	v_or_b32_e32 v10, 3, v10
	v_add_u32_e32 v118, 0x1400, v5
	v_or_b32_e32 v5, v115, v14
	s_mul_i32 s1, s1, 0x30000
	s_movk_i32 s23, 0x3000
	v_or_b32_e32 v17, v15, v17
	v_add_u32_e32 v13, 0, v13
	v_lshlrev_b32_e32 v22, 4, v2
	v_cmp_gt_u32_e64 s[10:11], v34, v11
	v_cmp_gt_u32_e64 s[12:13], v10, v11
	v_lshl_or_b32 v10, s16, 4, v11
	v_lshl_or_b32 v34, s16, 6, v111
	s_movk_i32 s16, 0x120
	v_add_u32_e32 v120, 0x1400, v5
	v_mov_b32_e32 v5, s1
	v_and_b32_e32 v22, 0xf0, v22
	v_mul_u32_u24_e32 v28, 0x60, v17
	v_mul_lo_u32 v30, v4, s24
	v_add_u32_e32 v112, s91, v32
	v_or_b32_e32 v32, s2, v11
	v_mad_u32_u24 v17, v17, s16, v13
	s_cselect_b64 s[16:17], -1, 0
	s_add_i32 s21, s25, s0
	v_mad_u32_u24 v5, v11, s23, v5
	v_mul_lo_u32 v16, v4, s23
	v_mul_u32_u24_e32 v21, 0x110, v11
	v_add_u32_e32 v22, 0, v22
	v_mul_lo_u32 v25, v24, s24
	v_mul_lo_u32 v27, v26, s24
	v_add_u32_e32 v30, 0, v30
	v_lshlrev_b32_e32 v2, 2, v4
	v_add_u32_e32 v31, 0, v111
	v_mul_u32_u24_e32 v32, 0x110, v32
	v_mul_u32_u24_e32 v10, 0x110, v10
	v_add_u32_e32 v38, s21, v15
	s_add_i32 s21, s36, 0x2080
	v_or3_b32 v121, v5, s2, v15
	v_ashrrev_i32_e32 v5, 31, v4
	v_readlane_b32 s80, v253, 61
	s_mov_b32 s26, 0x9300000
	v_add_u32_e32 v113, v112, v15
	v_or3_b32 v116, v16, v15, s2
	v_or_b32_e32 v117, 0x1400, v14
	v_lshl_add_u32 v119, v12, 1, s21
	v_lshlrev_b64 v[74:75], 2, v[4:5]
	v_add_u32_e32 v122, v19, v21
	v_add_u32_e32 v123, v36, v111
	v_add_u32_e32 v124, v38, v21
	v_add_u32_e32 v125, v35, v111
	v_add_u32_e32 v126, s3, v18
	v_add_u32_e32 v127, v22, v25
	v_add_u32_e32 v128, s36, v23
	v_add_u32_e32 v129, v22, v27
	v_add_u32_e32 v130, s20, v29
	v_add_u32_e32 v131, v30, v111
	v_add_u32_e32 v132, s3, v2
	v_add_u32_e32 v133, v31, v32
	v_add_u32_e32 v134, s3, v33
	v_add_u32_e32 v135, v31, v10
	v_add_u32_e32 v136, s3, v34
	v_add_u32_e32 v137, s0, v17
	v_add_u32_e32 v138, v13, v28
	v_add_u32_e32 v139, v20, v37
	v_lshrrev_b32_e32 v189, 4, v0
	v_and_b32_e32 v188, 15, v0
	s_movk_i32 s2, 0x120
	v_lshlrev_b32_e32 v188, 4, v188
	v_mad_u32_u24 v188, v189, s2, v188
	v_lshlrev_b32_e32 v189, 2, v189
	v_add_u32_e32 v190, 0x80, v189
	v_and_b32_e32 v76, 63, v0
	v_lshrrev_b32_e32 v77, 2, v76
	v_add_u32_e32 v77, s36, v77
	v_and_b32_e32 v76, 3, v76
	v_lshlrev_b32_e32 v76, 4, v76
	s_movk_i32 s2, 0x3000
	v_mad_u32_u24 v108, v77, s2, v76
	v_add_u32_e32 v108, 0x1000, v108
	s_movk_i32 s2, 0x60
	v_mad_u32_u24 v130, v77, s2, v76
	s_mov_b32 s72, s92
	s_mov_b32 s73, s92
	v_readlane_b32 s81, v253, 62
	s_branch .LBB0_710

; __device__ __forceinline__ void ssd_load(SsdRegs& R, const bf16_t* BIG, const float* DT, const SsdItem& I, int cc, int wave) {
;     const size_t r0 = (size_t)I.b * SEQ_ + (size_t)cc * 64;
;     const char* cb = (const char*)BIG + r0 * (BIGW * 2); const char* cd = (const char*)DT + r0 * 128;
; #pragma unroll
;     for (int i = 0; i < 2; ++i) { R.rb[i] = *(const uint4*)(cb + I.offB[i]); R.rc[i] = *(const uint4*)(cb + I.offC[i]); }
;     if (wave < 4) R.rx = *(const uint4*)(cb + I.offX);
;     R.rz = *(const u32x2*)(cb + I.offZ);
;     R.rdt = *(const float*)(cd + I.offDT);
; }
; template <bool DRY>
; __device__ __forceinline__ void phase_ssd_scan(const Args& a, int j, unsigned char* lds_raw) {
;     ...
;         const int xc = it & 7, slot = it >> 3, pair = xc + 8 * (slot >> 3), sub = slot & 7;
;         SsdItem I; I.b = pair >> 3; I.g = pair & 7; I.h = I.g * 4 + (sub >> 1); I.ph = sub & 1;
;         I.Ah = -__expf(A_log[I.h]); I.Dh = Dp[I.h];
; #pragma unroll
;         for (int i = 0; i < 2; ++i) { I.offB[i] = (unsigned)(lane * BIGW + 4096 + I.g * 128 + (wave + 8 * i) * 8) * 2u; const int id = tid + 512 * i; I.offC[i] = (unsigned)((id >> 4) * BIGW + 5120 + I.g * 128 + (id & 15) * 8) * 2u; }
;         I.offX = (unsigned)(lane * BIGW + DI_ + I.h * 64 + I.ph * 32 + wave * 8) * 2u;
;         I.offZ = (unsigned)((16 * li + c16) * BIGW + I.h * 64 + I.ph * 32 + 16 * pi + 4 * q4) * 2u;
;         I.offDT = (unsigned)(lane * 32 + I.h) * 4u;
;         f32x4 st[2]; st[0] = (f32x4){0.f, 0.f, 0.f, 0.f}; st[1] = (f32x4){0.f, 0.f, 0.f, 0.f};
;         SsdRegs R0, R1; R0.rx = make_uint4(0, 0, 0, 0); R1.rx = make_uint4(0, 0, 0, 0);
;         ssd_load(R0, BIG, DT, I, 0, wave);
;         ssd_load(R1, BIG, DT, I, 1, wave);
.LBB0_710:
	s_and_b32 s1, s73, 7
	s_lshl_b32 s2, s1, 2
	s_bfe_u32 s3, s73, 0x20004
	s_or_b32 s2, s2, s3
	s_lshl_b32 s3, s2, 2
	v_readlane_b32 s20, v255, 10
	s_waitcnt vmcnt(1)
	v_mov_b32_e32 v2, s3
	v_readlane_b32 s21, v255, 11
	s_lshl_b32 s1, s1, 7
	v_add_lshl_u32 v32, v1, s1, 1
	s_ashr_i32 s0, s73, 6
	s_lshl_b32 s74, s2, 7
	s_mul_i32 s22, s0, 0x3000000
	global_load_dword v52, v2, s[20:21]
	v_readlane_b32 s20, v255, 22
	v_readlane_b32 s21, v255, 23
	s_mul_hi_i32 s23, s0, 0x3000000
	v_add_u32_e32 v40, 0x80, v32
	v_readlane_b32 s24, v255, 24
	v_readlane_b32 s25, v255, 25
	s_nop 0
	global_load_dword v77, v2, s[20:21]
	v_or_b32_e32 v2, s1, v117
	s_lshl_b32 s1, s73, 3
	s_and_b32 s3, s1, 64
	s_or_b32 s1, s74, s3
	v_readlane_b32 s20, v253, 16
	v_readlane_b32 s21, v253, 17
	s_add_u32 s20, s20, s22
	s_addc_u32 s21, s21, s23
	v_add_lshl_u32 v30, v2, v114, 1
	v_add_lshl_u32 v38, v2, v115, 1
	s_nop 0
	global_load_dwordx4 v[10:13], v30, s[20:21] offset:-2048
	global_load_dwordx4 v[14:17], v30, s[20:21]
	global_load_dwordx4 v[18:21], v38, s[20:21] offset:-2048
	global_load_dwordx4 v[22:25], v38, s[20:21]
	v_add_u32_e32 v2, s1, v108
	s_andn2_b64 vcc, exec, s[24:25]
	s_cbranch_vccnz .LBB0_713
	v_mov_b64_e32 v[50:51], v[2:3]
	s_cbranch_execz .LBB0_714
	v_mov_b32_e32 v4, v3
	v_mov_b32_e32 v5, v3
	v_mov_b32_e32 v2, v3
	v_mov_b64_e32 v[28:29], v[4:5]
	v_mov_b64_e32 v[26:27], v[2:3]
	s_branch .LBB0_715

; __device__ __forceinline__ void ssd_load(SsdRegs& R, const bf16_t* BIG, const float* DT, const SsdItem& I, int cc, int wave) {
;     const size_t r0 = (size_t)I.b * SEQ_ + (size_t)cc * 64;
;     const char* cb = (const char*)BIG + r0 * (BIGW * 2); const char* cd = (const char*)DT + r0 * 128;
; #pragma unroll
;     for (int i = 0; i < 2; ++i) { R.rb[i] = *(const uint4*)(cb + I.offB[i]); R.rc[i] = *(const uint4*)(cb + I.offC[i]); }
;     if (wave < 4) R.rx = *(const uint4*)(cb + I.offX);
;     R.rz = *(const u32x2*)(cb + I.offZ);
;     R.rdt = *(const float*)(cd + I.offDT);
; }
.LBB0_715:
	s_ashr_i32 s1, s0, 31
	s_lshl_b64 s[82:83], s[0:1], 12
	s_lshl_b64 s[24:25], s[0:1], 19
	v_or_b32_e32 v2, s74, v116
	s_lshl_b32 s100, s2, s101
	v_or_b32_e32 v4, s100, v109
	s_add_u32 s2, s80, s24
	v_or_b32_e32 v2, s3, v2
	s_addc_u32 s3, s81, s25
	s_or_b32 s82, s82, 64
	global_load_dwordx2 v[96:97], v2, s[20:21]
	global_load_dword v140, v4, s[2:3]
	s_mul_i32 s2, s83, 0x3000
	s_mul_hi_u32 s3, s82, 0x3000
	s_add_i32 s3, s3, s2
	s_mul_i32 s2, s82, 0x3000
	v_readlane_b32 s20, v253, 16
	v_readlane_b32 s21, v253, 17
	s_add_u32 s86, s20, s2
	v_mov_b32_e32 v33, v3
	v_mov_b32_e32 v31, v3
	v_mov_b32_e32 v41, v3
	s_addc_u32 s87, s21, s3
	v_mov_b32_e32 v39, v3
	v_lshl_add_u64 v[32:33], s[86:87], 0, v[32:33]
	v_lshl_add_u64 v[34:35], s[86:87], 0, v[30:31]
	v_lshl_add_u64 v[40:41], s[86:87], 0, v[40:41]
	global_load_dwordx4 v[30:33], v[34:35], off offset:-2048
	s_nop 0
	global_load_dwordx4 v[34:37], v[34:35], off
	v_lshl_add_u64 v[38:39], s[86:87], 0, v[38:39]
	global_load_dwordx4 v[42:45], v[38:39], off offset:-2048
	global_load_dwordx4 v[46:49], v[38:39], off
	v_readlane_b32 s2, v255, 20
	v_readlane_b32 s3, v255, 21
	s_andn2_b64 vcc, exec, s[2:3]
	s_nop 0
	v_cndmask_b32_e64 v5, 0, 1, s[2:3]
	v_cmp_ne_u32_e64 s[20:21], 1, v5
	s_cbranch_vccnz .LBB0_717
	v_lshl_add_u64 v[38:39], s[86:87], 0, v[50:51]
	global_load_dwordx4 v[38:41], v[38:39], off
	s_branch .LBB0_718

; template <bool DRY>
; __device__ __forceinline__ void phase_ssd_scan(const Args& a, int j, unsigned char* lds_raw) {
;     ...
; #pragma unroll
;         for (int i = 0; i < 2; ++i) { I.offB[i] = (unsigned)(lane * BIGW + 4096 + I.g * 128 + (wave + 8 * i) * 8) * 2u; const int id = tid + 512 * i; I.offC[i] = (unsigned)((id >> 4) * BIGW + 5120 + I.g * 128 + (id & 15) * 8) * 2u; }
;         I.offX = (unsigned)(lane * BIGW + DI_ + I.h * 64 + I.ph * 32 + wave * 8) * 2u;
;         I.offZ = (unsigned)((16 * li + c16) * BIGW + I.h * 64 + I.ph * 32 + 16 * pi + 4 * q4) * 2u;
;         I.offDT = (unsigned)(lane * 32 + I.h) * 4u;
;         f32x4 st[2]; st[0] = (f32x4){0.f, 0.f, 0.f, 0.f}; st[1] = (f32x4){0.f, 0.f, 0.f, 0.f};
;         SsdRegs R0, R1; R0.rx = make_uint4(0, 0, 0, 0); R1.rx = make_uint4(0, 0, 0, 0);
;         ssd_load(R0, BIG, DT, I, 0, wave);
;         ssd_load(R1, BIG, DT, I, 1, wave);
.LBB0_718:
	s_lshr_b32 s2, s73, 4
	s_and_b32 s74, s72, 7
	s_and_b32 s2, s2, 3
	s_lshl_b32 s75, s74, 4
	s_lshl_b32 s78, s2, 2
	s_lshr_b32 s3, s73, 3
	s_or_b32 s80, s78, s75
	s_sub_u32 s100, s101, 2
	s_lshl_b32 s80, s80, s100
	v_add_u32_e32 v54, s80, v109
	s_lshl_b32 s80, s74, 7
	s_and_b32 s3, s3, 1
	v_add_lshl_u32 v56, v1, s80, 1
	v_add_lshl_u32 v58, v118, s80, 1
	v_add_lshl_u32 v62, v120, s80, 1
	s_lshl_b32 s2, s2, 7
	s_lshl_b32 s80, s3, 6
	v_lshl_add_u32 v60, s74, 8, v119
	s_lshl_b32 s74, s74, 9
	s_or_b32 s2, s80, s2
	s_or_b32 s2, s2, s74
	v_add_u32_e32 v64, s2, v121
	v_readlane_b32 s2, v255, 18
	s_or_b32 s2, s2, s75
	s_or_b32 s2, s2, s78
	s_lshl_b32 s2, s2, 16
	s_lshl_b32 s3, s3, 17
	s_or_b32 s74, s3, s2
	s_lshl_b64 s[2:3], s[82:83], 7
	v_readlane_b32 s80, v253, 61
	v_readlane_b32 s81, v253, 62
	s_add_u32 s2, s80, s2
	v_mov_b32_e32 v5, v3
	s_waitcnt vmcnt(11)
	v_mul_f32_e32 v52, 0x3fb8aa3b, v52
	s_addc_u32 s3, s81, s3
	v_exp_f32_e32 v141, v52
	v_lshl_add_u64 v[52:53], s[86:87], 0, v[2:3]
	v_lshl_add_u64 v[4:5], s[2:3], 0, v[4:5]
	global_load_dwordx2 v[92:93], v[52:53], off
	global_load_dword v2, v[4:5], off
	s_lshl_b64 s[0:1], s[0:1], 14
	s_add_u32 s0, s0, s74
	v_mov_b32_e32 v55, v3
	v_mov_b32_e32 v57, v3
	v_mov_b32_e32 v59, v3
	v_mov_b32_e32 v61, v3
	v_mov_b32_e32 v63, v3
	v_mov_b32_e32 v65, v3
	v_lshl_add_u64 v[86:87], v[50:51], 0, s[22:23]
	s_addc_u32 s1, s1, 0
	v_mov_b32_e32 v50, 0
	v_lshl_add_u64 v[4:5], s[24:25], 0, v[54:55]
	v_lshl_add_u64 v[78:79], s[22:23], 0, v[56:57]
	v_lshl_add_u64 v[80:81], s[22:23], 0, v[58:59]
	v_lshl_add_u64 v[82:83], s[22:23], 0, v[60:61]
	v_lshl_add_u64 v[84:85], s[22:23], 0, v[62:63]
	v_lshl_add_u64 v[88:89], s[22:23], 0, v[64:65]
	v_lshl_add_u64 v[90:91], s[0:1], 0, v[74:75]
	s_mov_b32 s2, 0
	v_mov_b32_e32 v51, v50
	v_mov_b32_e32 v52, v50
	v_mov_b32_e32 v53, v50
	v_mov_b32_e32 v54, v50
	v_mov_b32_e32 v55, v50
	v_mov_b32_e32 v56, v50
	v_mov_b32_e32 v57, v50
	v_mov_b32_e32 v58, v50
	v_mov_b32_e32 v59, v50
	v_mov_b32_e32 v61, v50
	v_mov_b32_e32 v60, v50
	v_mov_b32_e32 v62, v50
	v_mov_b32_e32 v63, v50
	v_mov_b32_e32 v64, v50
	v_readlane_b32 s78, v254, 59
	s_branch .LBB0_720

; #define LAS __attribute__((address_space(3)))
; __device__ __forceinline__ unsigned pk2(float lo, float hi) { unsigned r; asm volatile("v_cvt_pk_bf16_f32 %0, %1, %2" : "=v"(r) : "v"(lo), "v"(hi)); return r; }
; template <bool DRY>
; __device__ __forceinline__ void ssd_chunk(SsdRegs& R, f32x4 (&st)[2], LAS unsigned char* L, bf16_t* BIG, const float* DT, float* SSQY, const SsdItem& I, int c, int tid, int lane, int wave, int li, int pi, int c16, int q4) {
;     ...
;     const size_t row0 = (size_t)I.b * SEQ_ + (size_t)c * 64;
;     const float dtl = R.rdt;
;     float acs = dtl * I.Ah;
;     acs += dppz<0x111>(acs); acs += dppz<0x112>(acs); acs += dppz<0x114>(acs); acs += dppz<0x118>(acs);
;     acs += __builtin_bit_cast(float, __builtin_amdgcn_update_dpp(0, __builtin_bit_cast(int, acs), 0x142, 0xa, 0xf, false));
;     acs += __builtin_bit_cast(float, __builtin_amdgcn_update_dpp(0, __builtin_bit_cast(int, acs), 0x143, 0xc, 0xf, false));
;     const float tot = __builtin_bit_cast(float, __builtin_amdgcn_readlane(__builtin_bit_cast(int, acs), 63));
;     const float wl = dtl * __expf(tot - acs), etot = __expf(tot);
;     LAS unsigned char* SCW = L + SCT + wave * 512;
;     *(LAS float*)(SCW + lane * 4) = acs; *(LAS float*)(SCW + 256 + lane * 4) = dtl;
; #pragma unroll
;     for (int pt = 0; pt < 2; ++pt) { u32x2 w; w.x = pk2(st[pt][0], st[pt][1]); w.y = pk2(st[pt][2], st[pt][3]); *(LAS u32x2*)(L + SB + (16 * pt + c16) * PC + (16 * wave + 4 * q4) * 2) = w; }
; #pragma unroll
;     for (int i = 0; i < 2; ++i) {
;         const int id = tid + 512 * i; *(LAS u32x4*)(L + CS + (id >> 4) * PC + (id & 15) * 16) = (u32x4){R.rc[i].x, R.rc[i].y, R.rc[i].z, R.rc[i].w};
;         const int n8 = wave + 8 * i; *(LAS u32x4*)(L + BS + lane * PC + n8 * 16) = (u32x4){R.rb[i].x, R.rb[i].y, R.rb[i].z, R.rb[i].w};
;         float f[8]; unpack8(R.rb[i], f);
;         u32x4 bwv; bwv.x = pk2(f[0] * wl, f[1] * wl); bwv.y = pk2(f[2] * wl, f[3] * wl); bwv.z = pk2(f[4] * wl, f[5] * wl); bwv.w = pk2(f[6] * wl, f[7] * wl);
;         *(LAS u32x4*)(L + BW + lane * PB + n8 * 16) = bwv;
;     }
;     if (wave < 4) *(LAS u32x4*)(L + XI + lane * PX + wave * 16) = (u32x4){R.rx.x, R.rx.y, R.rx.z, R.rx.w};
;     const u32x2 zc = R.rz;
;     __syncthreads();
;     if (c + 2 < 64) ssd_load(R, BIG, DT, I, c + 2, wave);
.LBB0_720:
	s_waitcnt vmcnt(6)
	v_mul_f32_e64 v65, v140, -v141
	v_mov_b32_e32 v66, 0
	v_add_u32_e32 v142, s36, v110
	v_mov_b32_dpp v65, v65 row_shr:1 row_mask:0xf bank_mask:0xf bound_ctrl:1
	v_fma_f32 v65, v140, -v141, v65
	s_and_b64 vcc, exec, s[20:21]
	s_nop 0
	v_add_f32_dpp v65, v65, v65 row_shr:2 row_mask:0xf bank_mask:0xf bound_ctrl:1
	s_nop 1
	v_add_f32_dpp v65, v65, v65 row_shr:4 row_mask:0xf bank_mask:0xf bound_ctrl:1
	s_nop 1
	v_add_f32_dpp v65, v65, v65 row_shr:8 row_mask:0xf bank_mask:0xf bound_ctrl:1
	s_nop 1
	v_mov_b32_dpp v66, v65 row_bcast:15 row_mask:0xa bank_mask:0xf
	v_add_f32_e32 v65, v65, v66
	v_mov_b32_e32 v66, 0
	s_nop 1
	v_mov_b32_dpp v66, v65 row_bcast:31 row_mask:0xc bank_mask:0xf
	v_add_f32_e32 v65, v65, v66
	ds_write2st64_b32 v126, v65, v140 offset1:1
	v_readlane_b32 s3, v65, 63
	v_cvt_pk_bf16_f32 v58, v50, v58
	v_cvt_pk_bf16_f32 v59, v59, v61
	ds_write_b64 v122, v[58:59]
	v_cvt_pk_bf16_f32 v58, v60, v62
	v_cvt_pk_bf16_f32 v59, v63, v64
	s_nop 0
	v_sub_f32_e32 v66, s3, v65
	v_mul_f32_e32 v66, 0x3fb8aa3b, v66
	v_exp_f32_e32 v66, v66
	ds_write_b64 v122, v[58:59] offset:4352
	v_lshlrev_b32_e32 v58, 16, v10
	v_and_b32_e32 v59, 0xffff0000, v10
	v_mul_f32_e32 v62, v140, v66
	ds_bpermute_b32 v191, v189, v62
	ds_bpermute_b32 v192, v190, v62
	v_lshlrev_b32_e32 v60, 16, v11
	v_and_b32_e32 v61, 0xffff0000, v11
	ds_write_b128 v127, v[14:17]
	ds_write_b128 v127, v[10:13] offset:17408
	s_waitcnt lgkmcnt(2)
	v_mul_f32_e32 v58, v191, v58
	v_mul_f32_e32 v59, v191, v59
	v_lshlrev_b32_e32 v63, 16, v12
	v_and_b32_e32 v64, 0xffff0000, v12
	v_cvt_pk_bf16_f32 v58, v58, v59
	v_mul_f32_e32 v59, v191, v60
	v_mul_f32_e32 v60, v191, v61
	v_lshlrev_b32_e32 v65, 16, v13
	v_cvt_pk_bf16_f32 v59, v59, v60
	v_mul_f32_e32 v60, v191, v63
	v_mul_f32_e32 v61, v191, v64
	v_and_b32_e32 v66, 0xffff0000, v13
	v_cvt_pk_bf16_f32 v60, v60, v61
	v_mul_f32_e32 v61, v191, v65
	v_mul_f32_e32 v63, v191, v66
	v_cvt_pk_bf16_f32 v61, v61, v63
	ds_write_b128 v188, v[58:61] offset:34816
	ds_write_b128 v129, v[22:25]
	ds_write_b128 v129, v[18:21] offset:17408
	v_lshlrev_b32_e32 v58, 16, v18
	v_and_b32_e32 v59, 0xffff0000, v18
	v_lshlrev_b32_e32 v60, 16, v19
	v_and_b32_e32 v61, 0xffff0000, v19
	v_mul_f32_e32 v58, v192, v58
	v_mul_f32_e32 v59, v192, v59
	v_lshlrev_b32_e32 v63, 16, v20
	v_and_b32_e32 v64, 0xffff0000, v20
	v_cvt_pk_bf16_f32 v58, v58, v59
	v_mul_f32_e32 v59, v192, v60
	v_mul_f32_e32 v60, v192, v61
	v_lshlrev_b32_e32 v65, 16, v21
	v_cvt_pk_bf16_f32 v59, v59, v60
	v_mul_f32_e32 v60, v192, v63
	v_mul_f32_e32 v61, v192, v64
	v_and_b32_e32 v66, 0xffff0000, v21
	v_cvt_pk_bf16_f32 v60, v60, v61
	v_mul_f32_e32 v61, v192, v65
	v_mul_f32_e32 v62, v192, v66
	v_cvt_pk_bf16_f32 v61, v61, v62
	ds_write_b128 v188, v[58:61] offset:44032
	s_cbranch_vccnz .LBB0_722
	ds_write_b128 v130, v[26:29] offset:53248
.LBB0_722:
	s_cmp_lt_u32 s2, 62
	s_cselect_b64 s[82:83], -1, 0
	s_cmp_gt_u32 s2, 61
	s_cselect_b64 s[86:87], -1, 0
	s_and_b64 vcc, exec, s[86:87]
	v_lshl_add_u64 v[104:105], s[30:31], 0, v[78:79]
	v_lshl_add_u64 v[102:103], s[30:31], 0, v[80:81]
	v_lshl_add_u64 v[100:101], s[30:31], 0, v[82:83]
	v_lshl_add_u64 v[98:99], s[30:31], 0, v[84:85]
	s_waitcnt lgkmcnt(0)
	s_barrier
	s_cbranch_vccnz .LBB0_726
	v_add_co_u32_e32 v10, vcc, 0x9480000, v104
	s_nop 1
	v_addc_co_u32_e32 v11, vcc, 0, v105, vcc
	v_add_co_u32_e32 v14, vcc, 0x9480000, v102
	s_nop 1
	v_addc_co_u32_e32 v15, vcc, 0, v103, vcc
	v_add_co_u32_e32 v18, vcc, 0x9480000, v100
	global_load_dwordx4 v[10:13], v[14:15], off offset:-2048
	s_nop 0
	global_load_dwordx4 v[14:17], v[14:15], off
	v_addc_co_u32_e32 v19, vcc, 0, v101, vcc
	v_add_co_u32_e32 v22, vcc, 0x9480000, v98
	s_nop 1
	v_addc_co_u32_e32 v23, vcc, 0, v99, vcc
	global_load_dwordx4 v[18:21], v[22:23], off offset:-2048
	s_nop 0
	global_load_dwordx4 v[22:25], v[22:23], off
	s_and_b64 vcc, exec, s[20:21]
	s_cbranch_vccnz .LBB0_725
	v_lshl_add_u64 v[26:27], s[30:31], 0, v[86:87]
	v_add_co_u32_e32 v26, vcc, 0x9480000, v26
	s_nop 1
	v_addc_co_u32_e32 v27, vcc, 0, v27, vcc
	global_load_dwordx4 v[26:29], v[26:27], off

; #define LAS __attribute__((address_space(3)))
; __device__ __forceinline__ unsigned pk2(float lo, float hi) { unsigned r; asm volatile("v_cvt_pk_bf16_f32 %0, %1, %2" : "=v"(r) : "v"(lo), "v"(hi)); return r; }
; template <bool DRY>
; __device__ __forceinline__ void ssd_chunk(SsdRegs& R, f32x4 (&st)[2], LAS unsigned char* L, bf16_t* BIG, const float* DT, float* SSQY, const SsdItem& I, int c, int tid, int lane, int wave, int li, int pi, int c16, int q4) {
;     ...
;     const size_t row0 = (size_t)I.b * SEQ_ + (size_t)c * 64;
;     const float dtl = R.rdt;
;     float acs = dtl * I.Ah;
;     acs += dppz<0x111>(acs); acs += dppz<0x112>(acs); acs += dppz<0x114>(acs); acs += dppz<0x118>(acs);
;     acs += __builtin_bit_cast(float, __builtin_amdgcn_update_dpp(0, __builtin_bit_cast(int, acs), 0x142, 0xa, 0xf, false));
;     acs += __builtin_bit_cast(float, __builtin_amdgcn_update_dpp(0, __builtin_bit_cast(int, acs), 0x143, 0xc, 0xf, false));
;     const float tot = __builtin_bit_cast(float, __builtin_amdgcn_readlane(__builtin_bit_cast(int, acs), 63));
;     const float wl = dtl * __expf(tot - acs), etot = __expf(tot);
;     LAS unsigned char* SCW = L + SCT + wave * 512;
;     *(LAS float*)(SCW + lane * 4) = acs; *(LAS float*)(SCW + 256 + lane * 4) = dtl;
; #pragma unroll
;     for (int pt = 0; pt < 2; ++pt) { u32x2 w; w.x = pk2(st[pt][0], st[pt][1]); w.y = pk2(st[pt][2], st[pt][3]); *(LAS u32x2*)(L + SB + (16 * pt + c16) * PC + (16 * wave + 4 * q4) * 2) = w; }
; #pragma unroll
;     for (int i = 0; i < 2; ++i) {
;         const int id = tid + 512 * i; *(LAS u32x4*)(L + CS + (id >> 4) * PC + (id & 15) * 16) = (u32x4){R.rc[i].x, R.rc[i].y, R.rc[i].z, R.rc[i].w};
;         const int n8 = wave + 8 * i; *(LAS u32x4*)(L + BS + lane * PC + n8 * 16) = (u32x4){R.rb[i].x, R.rb[i].y, R.rb[i].z, R.rb[i].w};
;         float f[8]; unpack8(R.rb[i], f);
;         u32x4 bwv; bwv.x = pk2(f[0] * wl, f[1] * wl); bwv.y = pk2(f[2] * wl, f[3] * wl); bwv.z = pk2(f[4] * wl, f[5] * wl); bwv.w = pk2(f[6] * wl, f[7] * wl);
;         *(LAS u32x4*)(L + BW + lane * PB + n8 * 16) = bwv;
;     }
;     if (wave < 4) *(LAS u32x4*)(L + XI + lane * PX + wave * 16) = (u32x4){R.rx.x, R.rx.y, R.rx.z, R.rx.w};
;     const u32x2 zc = R.rz;
;     __syncthreads();
;     if (c + 2 < 64) ssd_load(R, BIG, DT, I, c + 2, wave);
.LBB0_735:
	s_or_b64 exec, exec, s[0:1]
	s_waitcnt vmcnt(1)
	v_mul_f32_e64 v58, v2, -v141
	s_waitcnt lgkmcnt(0)
	v_mov_b32_e32 v59, 0
	v_and_b32_e32 v61, 0xffff0000, v31
	v_mov_b32_dpp v58, v58 row_shr:1 row_mask:0xf bank_mask:0xf bound_ctrl:1
	v_fma_f32 v58, v2, -v141, v58
	v_lshlrev_b32_e32 v63, 16, v32
	v_and_b32_e32 v64, 0xffff0000, v32
	v_add_f32_dpp v58, v58, v58 row_shr:2 row_mask:0xf bank_mask:0xf bound_ctrl:1
	v_lshlrev_b32_e32 v65, 16, v33
	v_and_b32_e32 v66, 0xffff0000, v33
	v_add_f32_dpp v58, v58, v58 row_shr:4 row_mask:0xf bank_mask:0xf bound_ctrl:1
	s_and_b64 vcc, exec, s[20:21]
	s_nop 0
	v_add_f32_dpp v58, v58, v58 row_shr:8 row_mask:0xf bank_mask:0xf bound_ctrl:1
	s_nop 1
	v_mov_b32_dpp v59, v58 row_bcast:15 row_mask:0xa bank_mask:0xf
	v_add_f32_e32 v58, v58, v59
	v_mov_b32_e32 v59, 0
	s_nop 1
	v_mov_b32_dpp v59, v58 row_bcast:31 row_mask:0xc bank_mask:0xf
	v_add_f32_e32 v58, v58, v59
	ds_write2st64_b32 v126, v58, v2 offset1:1
	v_readlane_b32 s3, v58, 63
	s_nop 1
	v_sub_f32_e32 v59, s3, v58
	v_mul_f32_e32 v59, 0x3fb8aa3b, v59
	v_exp_f32_e32 v60, v59
	v_cvt_pk_bf16_f32 v58, v50, v51
	v_cvt_pk_bf16_f32 v59, v52, v53
	ds_write_b64 v124, v[58:59]
	v_cvt_pk_bf16_f32 v58, v54, v55
	v_cvt_pk_bf16_f32 v59, v56, v57
	ds_write_b64 v124, v[58:59] offset:4352
	v_mul_f32_e32 v62, v2, v60
	ds_bpermute_b32 v191, v189, v62
	ds_bpermute_b32 v192, v190, v62
	v_lshlrev_b32_e32 v58, 16, v30
	v_and_b32_e32 v59, 0xffff0000, v30
	v_lshlrev_b32_e32 v60, 16, v31
	ds_write_b128 v127, v[34:37]
	ds_write_b128 v127, v[30:33] offset:17408
	s_waitcnt lgkmcnt(2)
	v_mul_f32_e32 v58, v191, v58
	v_mul_f32_e32 v59, v191, v59
	v_cvt_pk_bf16_f32 v58, v58, v59
	v_mul_f32_e32 v59, v191, v60
	v_mul_f32_e32 v60, v191, v61
	v_cvt_pk_bf16_f32 v59, v59, v60
	v_mul_f32_e32 v60, v191, v63
	v_mul_f32_e32 v61, v191, v64
	v_cvt_pk_bf16_f32 v60, v60, v61
	v_mul_f32_e32 v61, v191, v65
	v_mul_f32_e32 v63, v191, v66
	v_cvt_pk_bf16_f32 v61, v61, v63
	ds_write_b128 v188, v[58:61] offset:34816
	ds_write_b128 v129, v[46:49]
	ds_write_b128 v129, v[42:45] offset:17408
	v_lshlrev_b32_e32 v58, 16, v42
	v_and_b32_e32 v59, 0xffff0000, v42
	v_lshlrev_b32_e32 v60, 16, v43
	v_and_b32_e32 v61, 0xffff0000, v43
	v_mul_f32_e32 v58, v192, v58
	v_mul_f32_e32 v59, v192, v59
	v_lshlrev_b32_e32 v63, 16, v44
	v_and_b32_e32 v64, 0xffff0000, v44
	v_cvt_pk_bf16_f32 v58, v58, v59
	v_mul_f32_e32 v59, v192, v60
	v_mul_f32_e32 v60, v192, v61
	v_lshlrev_b32_e32 v65, 16, v45
	v_cvt_pk_bf16_f32 v59, v59, v60
	v_mul_f32_e32 v60, v192, v63
	v_mul_f32_e32 v61, v192, v64
	v_and_b32_e32 v66, 0xffff0000, v45
	v_cvt_pk_bf16_f32 v60, v60, v61
	v_mul_f32_e32 v61, v192, v65
	v_mul_f32_e32 v62, v192, v66
	v_cvt_pk_bf16_f32 v61, v61, v62
	ds_write_b128 v188, v[58:61] offset:44032
	s_cbranch_vccnz .LBB0_737
	ds_write_b128 v130, v[38:41] offset:59392
.LBB0_737:
	s_andn2_b64 vcc, exec, s[82:83]
	s_waitcnt lgkmcnt(0)
	s_barrier
	s_cbranch_vccnz .LBB0_741
	v_add_co_u32_e32 v30, vcc, 0x9540000, v104
	s_nop 1
	v_addc_co_u32_e32 v31, vcc, 0, v105, vcc
	v_add_co_u32_e32 v34, vcc, 0x9540000, v102
	s_nop 1
	v_addc_co_u32_e32 v35, vcc, 0, v103, vcc
	v_add_co_u32_e32 v42, vcc, 0x9540000, v100
	global_load_dwordx4 v[30:33], v[34:35], off offset:-2048
	s_nop 0
	global_load_dwordx4 v[34:37], v[34:35], off
	v_addc_co_u32_e32 v43, vcc, 0, v101, vcc
	v_add_co_u32_e32 v46, vcc, 0x9540000, v98
	s_nop 1
	v_addc_co_u32_e32 v47, vcc, 0, v99, vcc
	global_load_dwordx4 v[42:45], v[46:47], off offset:-2048
	s_nop 0
	global_load_dwordx4 v[46:49], v[46:47], off
	s_and_b64 vcc, exec, s[20:21]
	s_cbranch_vccnz .LBB0_740
	v_lshl_add_u64 v[38:39], s[30:31], 0, v[86:87]
	v_add_co_u32_e32 v38, vcc, 0x9540000, v38
	s_nop 1
	v_addc_co_u32_e32 v39, vcc, 0, v39, vcc
	global_load_dwordx4 v[38:41], v[38:39], off

; __device__ __forceinline__ float softplus_f(float x) { return x > 20.f ? x : log1pf(__expf(x)); }
; __device__ __forceinline__ float rsx(const float* ssqx, int row) { const f32x4 p = *(const f32x4*)(ssqx + (size_t)row * 4); return rsqrtf(((p[0] + p[1]) + (p[2] + p[3])) * (1.0f / 1024.f) + EPS_); }
; __device__ __forceinline__ void phase_ssd_conv_dt(const Args& a, int j) {
;     ...
;     if (has_dt) {
;         const float* RSX = (const float*)(a.ws + WS_RSX); float* DT = (float*)(a.ws + WS_DT); const float* dt_bias = a.in[8] + j * 32;
;         const int row = drow0 + c16; const float s = rsx(RSX, row);
;         const f32x4 b0 = *(const f32x4*)(dt_bias + 4 * q4), b1 = *(const f32x4*)(dt_bias + 16 + 4 * q4);
;         f32x4 o0, o1;
; #pragma unroll
;         for (int e = 0; e < 4; ++e) { o0[e] = softplus_f(d0[e] * s + b0[e]); o1[e] = softplus_f(d1[e] * s + b1[e]); }
;         *(f32x4*)(DT + (size_t)row * 32 + 4 * q4) = o0; *(f32x4*)(DT + (size_t)row * 32 + 16 + 4 * q4) = o1;
;     }
.LBB0_820:
	s_or_b64 exec, exec, s[0:1]
	v_lshrrev_b32_e32 v1, 4, v100
	v_readlane_b32 s0, v253, 61
	v_readlane_b32 s1, v253, 62
	v_lshrrev_b32_e32 v2, 6, v62
	v_and_b32_e32 v4, 63, v62
	v_lshlrev_b32_e32 v2, 13, v2
	v_lshl_add_u32 v2, v4, 2, v2
	v_lshl_add_u32 v2, v1, 10, v2
	v_add_u32_e32 v2, 0x800, v2
	v_lshl_add_u64 v[4:5], s[0:1], 0, v[2:3]
	global_store_dword v[4:5], v22, off offset:-2048
	global_store_dword v[4:5], v23, off offset:-1792
	global_store_dword v[4:5], v24, off offset:-1536
	global_store_dword v[4:5], v25, off offset:-1280
	global_store_dword v[4:5], v18, off offset:2048
	global_store_dword v[4:5], v19, off offset:2304
	global_store_dword v[4:5], v20, off offset:2560
	global_store_dword v[4:5], v21, off offset:2816
